# chain loops: drop dead SGPR spill reloads, move loop-invariant reloads to loop exit
# baseline (speedup 1.0000x reference)
.LBB0_318:
	s_add_i32 s18, s19, 1
	s_cmp_lt_u32 s18, s1
	s_cselect_b64 s[4:5], -1, 0
	s_cmp_ge_u32 s18, s1
	s_cbranch_scc1 .LBB0_320
	s_add_i32 s20, s16, -1
	s_and_b64 s[6:7], s[38:39], exec
	s_cselect_b32 s6, s18, s20
	s_add_i32 s23, s6, s15
	s_lshl_b32 s6, s23, 3
	s_or_b32 s6, s6, s17
	s_ashr_i32 s7, s6, 31
	s_lshl_b64 s[20:21], s[6:7], 14
	v_readlane_b32 s58, v246, 63
	v_readlane_b32 s59, v245, 0
	s_add_u32 s24, s58, s20
	s_addc_u32 s25, s59, s21
	v_lshl_add_u64 v[32:33], v[68:69], 1, s[24:25]
	v_lshl_add_u64 v[36:37], v[70:71], 1, s[24:25]
	v_lshl_add_u64 v[40:41], v[72:73], 1, s[24:25]
	v_lshl_add_u64 v[44:45], v[74:75], 1, s[24:25]
	v_lshl_add_u64 v[48:49], v[86:87], 0, s[20:21]
	s_lshl_b32 s20, s23, 6
	global_load_dwordx4 v[32:35], v[32:33], off
	v_readlane_b32 s60, v245, 1
	global_load_dwordx4 v[36:39], v[36:37], off
	s_lshl_b64 s[6:7], s[6:7], 2
	global_load_dwordx4 v[40:43], v[40:41], off
	v_readlane_b32 s61, v245, 2
	global_load_dwordx4 v[44:47], v[44:45], off
	s_nop 0
	global_load_dwordx2 v[96:97], v[48:49], off
	global_load_dwordx2 v[98:99], v[48:49], off offset:32
	global_load_dwordx2 v[100:101], v[48:49], off offset:64
	global_load_dwordx2 v[102:103], v[48:49], off offset:96
	global_load_dwordx2 v[104:105], v[48:49], off offset:128
	global_load_dwordx2 v[106:107], v[48:49], off offset:160
	global_load_dwordx2 v[108:109], v[48:49], off offset:192
	global_load_dwordx2 v[110:111], v[48:49], off offset:224
	v_or_b32_e32 v48, s20, v112
	v_ashrrev_i32_e32 v49, 31, v48
	v_lshlrev_b64 v[48:49], 10, v[48:49]
	v_lshl_add_u64 v[48:49], v[76:77], 0, v[48:49]
	global_load_dword v162, v[48:49], off
	v_or_b32_e32 v48, s20, v113
	v_ashrrev_i32_e32 v49, 31, v48
	v_lshlrev_b64 v[48:49], 10, v[48:49]
	v_lshl_add_u64 v[48:49], v[76:77], 0, v[48:49]
	global_load_dword v163, v[48:49], off
	v_or_b32_e32 v48, s20, v114
	v_ashrrev_i32_e32 v49, 31, v48
	v_lshlrev_b64 v[48:49], 10, v[48:49]
	v_lshl_add_u64 v[48:49], v[76:77], 0, v[48:49]
	global_load_dword v164, v[48:49], off
	v_or_b32_e32 v48, s20, v115
	v_ashrrev_i32_e32 v49, 31, v48
	v_lshlrev_b64 v[48:49], 10, v[48:49]
	v_lshl_add_u64 v[48:49], v[76:77], 0, v[48:49]
	global_load_dword v165, v[48:49], off
	v_or_b32_e32 v48, s20, v116
	v_ashrrev_i32_e32 v49, 31, v48
	v_lshlrev_b64 v[48:49], 10, v[48:49]
	v_lshl_add_u64 v[48:49], v[76:77], 0, v[48:49]
	global_load_dword v166, v[48:49], off
	v_or_b32_e32 v48, s20, v117
	v_ashrrev_i32_e32 v49, 31, v48
	v_lshlrev_b64 v[48:49], 10, v[48:49]
	v_lshl_add_u64 v[48:49], v[76:77], 0, v[48:49]
	global_load_dword v167, v[48:49], off
	v_or_b32_e32 v48, s20, v118
	v_ashrrev_i32_e32 v49, 31, v48
	v_lshlrev_b64 v[48:49], 10, v[48:49]
	v_lshl_add_u64 v[48:49], v[76:77], 0, v[48:49]
	global_load_dword v202, v[48:49], off
	v_or_b32_e32 v48, s20, v119
	v_ashrrev_i32_e32 v49, 31, v48
	v_lshlrev_b64 v[48:49], 10, v[48:49]
	v_lshl_add_u64 v[48:49], v[76:77], 0, v[48:49]
	global_load_dword v203, v[48:49], off
	v_or_b32_e32 v48, s20, v120
	v_ashrrev_i32_e32 v49, 31, v48
	v_lshlrev_b64 v[48:49], 10, v[48:49]
	v_lshl_add_u64 v[48:49], v[76:77], 0, v[48:49]
	global_load_dword v204, v[48:49], off
	v_or_b32_e32 v48, s20, v121
	v_ashrrev_i32_e32 v49, 31, v48
	v_lshlrev_b64 v[48:49], 10, v[48:49]
	v_lshl_add_u64 v[48:49], v[76:77], 0, v[48:49]
	global_load_dword v205, v[48:49], off
	v_or_b32_e32 v48, s20, v122
	v_ashrrev_i32_e32 v49, 31, v48
	v_lshlrev_b64 v[48:49], 10, v[48:49]
	v_lshl_add_u64 v[48:49], v[76:77], 0, v[48:49]
	global_load_dword v208, v[48:49], off
	v_or_b32_e32 v48, s20, v123
	v_ashrrev_i32_e32 v49, 31, v48
	v_lshlrev_b64 v[48:49], 10, v[48:49]
	v_lshl_add_u64 v[48:49], v[76:77], 0, v[48:49]
	global_load_dword v210, v[48:49], off
	v_or_b32_e32 v48, s20, v124
	v_ashrrev_i32_e32 v49, 31, v48
	v_lshlrev_b64 v[48:49], 10, v[48:49]
	v_lshl_add_u64 v[48:49], v[76:77], 0, v[48:49]
	global_load_dword v212, v[48:49], off
	v_or_b32_e32 v48, s20, v125
	v_ashrrev_i32_e32 v49, 31, v48
	v_lshlrev_b64 v[48:49], 10, v[48:49]
	v_lshl_add_u64 v[48:49], v[76:77], 0, v[48:49]
	global_load_dword v213, v[48:49], off
	v_or_b32_e32 v48, s20, v126
	v_ashrrev_i32_e32 v49, 31, v48
	v_lshlrev_b64 v[48:49], 10, v[48:49]
	v_lshl_add_u64 v[48:49], v[76:77], 0, v[48:49]
	global_load_dword v215, v[48:49], off
	v_or_b32_e32 v48, s20, v127
	v_ashrrev_i32_e32 v49, 31, v48
	v_lshlrev_b64 v[48:49], 10, v[48:49]
	s_add_u32 s6, s60, s6
	v_lshl_add_u64 v[48:49], v[76:77], 0, v[48:49]
	s_addc_u32 s7, s61, s7
	global_load_dword v220, v[48:49], off
	global_load_dword v219, v137, s[6:7]

.LBB0_322:
	v_readlane_b32 s52, v246, 57
	v_readlane_b32 s53, v246, 58
	v_readlane_b32 s54, v246, 59
	v_readlane_b32 s55, v246, 60
	v_readlane_b32 s56, v246, 61
	v_readlane_b32 s57, v246, 62
	v_readlane_b32 s62, v245, 3
	v_readlane_b32 s63, v245, 4
	v_readlane_b32 s64, v245, 5
	v_readlane_b32 s65, v245, 6
	v_readlane_b32 s66, v245, 7
	v_readlane_b32 s67, v245, 8
	s_and_b64 vcc, exec, s[2:3]
	s_cbranch_vccz .LBB0_325
	s_ashr_i32 s1, s0, 31
	s_lshl_b64 s[0:1], s[0:1], 3
	s_add_u32 s0, s0, s34
	s_addc_u32 s1, s1, s35
	s_or_b32 s0, s0, s14
	s_lshl_b64 s[0:1], s[0:1], 17
	v_readlane_b32 s2, v245, 54
	s_add_u32 s0, s2, s0
	v_readlane_b32 s2, v245, 55
	s_addc_u32 s1, s2, s1
	s_lshl_b32 s2, s13, 15
	s_add_u32 s0, s0, s2
	s_addc_u32 s1, s1, 0
	v_lshl_add_u64 v[32:33], v[64:65], 2, s[0:1]
	v_lshl_add_u64 v[32:33], v[66:67], 2, v[32:33]
	global_store_dwordx4 v[32:33], v[0:3], off
	global_store_dwordx4 v[32:33], v[28:31], off offset:64
	global_store_dwordx4 v[32:33], v[24:27], off offset:128
	global_store_dwordx4 v[32:33], v[20:23], off offset:192
	global_store_dwordx4 v[32:33], v[16:19], off offset:256
	global_store_dwordx4 v[32:33], v[12:15], off offset:320
	global_store_dwordx4 v[32:33], v[8:11], off offset:384
	global_store_dwordx4 v[32:33], v[4:7], off offset:448
	s_cbranch_execnz .LBB0_216
	s_branch .LBB0_326

.LBB0_330:
	s_add_i32 s16, s18, 1
	s_cmp_lt_u32 s16, s1
	s_cselect_b64 s[4:5], -1, 0
	s_cmp_ge_u32 s16, s1
	s_cbranch_scc1 .LBB0_332
	s_add_i32 s17, s14, -1
	s_and_b64 s[20:21], s[68:69], exec
	s_cselect_b32 s17, s16, s17
	s_add_i32 s17, s17, s13
	s_lshl_b32 s17, s17, 3
	s_or_b32 s20, s17, s15
	s_ashr_i32 s21, s20, 31
	s_lshl_b64 s[24:25], s[20:21], 13
	v_readlane_b32 s50, v246, 51
	v_readlane_b32 s51, v246, 52
	s_add_u32 s26, s50, s24
	v_readlane_b32 s52, v246, 53
	s_addc_u32 s27, s51, s25
	v_readlane_b32 s53, v246, 54
	v_lshl_add_u64 v[16:17], s[26:27], 0, v[72:73]
	v_lshl_add_u64 v[20:21], s[26:27], 0, v[74:75]
	s_add_u32 s26, s52, s24
	v_readlane_b32 s54, v246, 55
	s_addc_u32 s27, s53, s25
	v_readlane_b32 s55, v246, 56
	v_lshl_add_u64 v[24:25], s[26:27], 0, v[72:73]
	v_lshl_add_u64 v[28:29], s[26:27], 0, v[74:75]
	s_add_u32 s26, s54, s24
	s_addc_u32 s27, s55, s25
	v_readlane_b32 s36, v246, 57
	v_lshl_add_u64 v[32:33], s[26:27], 0, v[72:73]
	v_lshl_add_u64 v[36:37], s[26:27], 0, v[74:75]
	v_readlane_b32 s37, v246, 58
	s_add_u32 s26, s36, s24
	s_addc_u32 s27, s37, s25
	v_readlane_b32 s38, v246, 59
	v_lshl_add_u64 v[40:41], s[26:27], 0, v[72:73]
	v_lshl_add_u64 v[44:45], s[26:27], 0, v[74:75]
	v_lshl_add_u64 v[50:51], v[78:79], 0, s[24:25]
	s_lshl_b64 s[20:21], s[20:21], 2
	global_load_dwordx4 v[16:19], v[16:17], off
	s_nop 0
	global_load_dwordx4 v[20:23], v[20:21], off
	s_nop 0
	global_load_dwordx4 v[24:27], v[24:25], off
	s_nop 0
	global_load_dwordx4 v[28:31], v[28:29], off
	s_nop 0
	global_load_dwordx4 v[32:35], v[32:33], off
	s_nop 0
	global_load_dwordx4 v[36:39], v[36:37], off
	v_readlane_b32 s39, v246, 60
	global_load_dwordx4 v[40:43], v[40:41], off
	s_nop 0
	global_load_dwordx4 v[44:47], v[44:45], off
	s_nop 0
	global_load_dwordx2 v[80:81], v[50:51], off
	global_load_dwordx2 v[82:83], v[50:51], off offset:32
	global_load_dwordx2 v[84:85], v[50:51], off offset:64
	global_load_dwordx2 v[86:87], v[50:51], off offset:96
	s_add_u32 s20, s38, s20
	s_addc_u32 s21, s39, s21
	global_load_dword v127, v137, s[20:21]
	s_movk_i32 s36, 0x880
	v_readlane_b32 s50, v245, 7
	v_readlane_b32 s51, v245, 8

.LBB0_334:
	v_readlane_b32 s40, v246, 61
	v_readlane_b32 s41, v246, 62
	v_readlane_b32 s42, v246, 63
	v_readlane_b32 s43, v245, 0
	v_readlane_b32 s44, v245, 1
	v_readlane_b32 s45, v245, 2
	v_readlane_b32 s46, v245, 3
	v_readlane_b32 s47, v245, 4
	v_readlane_b32 s48, v245, 5
	v_readlane_b32 s49, v245, 6
	s_and_b64 vcc, exec, s[2:3]
	s_mov_b32 s68, s10
	s_cbranch_vccz .LBB0_216
	s_ashr_i32 s1, s0, 31
	s_lshl_b64 s[0:1], s[0:1], 3
	s_add_u32 s0, s0, s34
	s_addc_u32 s1, s1, s35
	s_or_b32 s0, s0, s7
	s_lshl_b64 s[0:1], s[0:1], 16
	v_readlane_b32 s2, v245, 56
	s_add_u32 s0, s2, s0
	v_readlane_b32 s2, v245, 57
	s_addc_u32 s1, s2, s1
	s_lshl_b32 s2, s6, 14
	s_add_u32 s0, s0, s2
	s_addc_u32 s1, s1, 0
	v_lshl_add_u64 v[16:17], v[70:71], 2, s[0:1]
	global_store_dword v[16:17], v12, off
	v_lshl_add_u32 v16, v101, 6, v68
	v_ashrrev_i32_e32 v17, 31, v16
	v_lshl_add_u64 v[16:17], v[16:17], 2, s[0:1]
	v_lshl_add_u32 v12, v99, 6, v68
	global_store_dword v[16:17], v13, off
	v_ashrrev_i32_e32 v13, 31, v12
	v_lshl_add_u64 v[12:13], v[12:13], 2, s[0:1]
	global_store_dword v[12:13], v14, off
	v_lshl_add_u32 v12, v107, 6, v68
	v_ashrrev_i32_e32 v13, 31, v12
	v_lshl_add_u64 v[12:13], v[12:13], 2, s[0:1]
	global_store_dword v[12:13], v15, off
	v_lshl_add_u32 v12, v106, 6, v68
	v_ashrrev_i32_e32 v13, 31, v12
	v_lshl_add_u64 v[12:13], v[12:13], 2, s[0:1]
	global_store_dword v[12:13], v0, off
	v_lshl_add_u32 v12, v105, 6, v68
	v_ashrrev_i32_e32 v13, 31, v12
	v_lshl_add_u64 v[12:13], v[12:13], 2, s[0:1]
	v_lshl_add_u32 v0, v104, 6, v68
	global_store_dword v[12:13], v1, off
	v_ashrrev_i32_e32 v1, 31, v0
	v_lshl_add_u64 v[0:1], v[0:1], 2, s[0:1]
	global_store_dword v[0:1], v2, off
	v_lshl_add_u32 v0, v103, 6, v68
	v_ashrrev_i32_e32 v1, 31, v0
	v_lshl_add_u64 v[0:1], v[0:1], 2, s[0:1]
	global_store_dword v[0:1], v3, off
	v_lshl_add_u32 v0, v102, 6, v68
	v_ashrrev_i32_e32 v1, 31, v0
	v_lshl_add_u64 v[0:1], v[0:1], 2, s[0:1]
	global_store_dword v[0:1], v8, off
	v_lshl_add_u32 v0, v100, 6, v68
	v_ashrrev_i32_e32 v1, 31, v0
	v_lshl_add_u64 v[0:1], v[0:1], 2, s[0:1]
	global_store_dword v[0:1], v9, off
	v_lshl_add_u32 v0, v98, 6, v68
	v_ashrrev_i32_e32 v1, 31, v0
	v_lshl_add_u64 v[0:1], v[0:1], 2, s[0:1]
	global_store_dword v[0:1], v10, off
	v_lshl_add_u32 v0, v97, 6, v68
	v_ashrrev_i32_e32 v1, 31, v0
	v_lshl_add_u64 v[0:1], v[0:1], 2, s[0:1]
	global_store_dword v[0:1], v11, off
	v_lshl_add_u32 v0, v96, 6, v68
	v_ashrrev_i32_e32 v1, 31, v0
	v_lshl_add_u64 v[0:1], v[0:1], 2, s[0:1]
	global_store_dword v[0:1], v4, off
	v_lshl_add_u32 v0, v95, 6, v68
	v_ashrrev_i32_e32 v1, 31, v0
	v_lshl_add_u64 v[0:1], v[0:1], 2, s[0:1]
	global_store_dword v[0:1], v5, off
	v_lshl_add_u32 v0, v94, 6, v68
	v_ashrrev_i32_e32 v1, 31, v0
	v_lshl_add_u64 v[0:1], v[0:1], 2, s[0:1]
	global_store_dword v[0:1], v6, off
	v_lshl_add_u32 v0, v69, 6, v68
	v_ashrrev_i32_e32 v1, 31, v0
	v_lshl_add_u64 v[0:1], v[0:1], 2, s[0:1]
	global_store_dword v[0:1], v7, off
	s_branch .LBB0_216
